# baseline (speedup 1.0000x reference)
; template <int MODE, int N>
; __device__ __forceinline__ void gemm_phase(const bf16_t* __restrict__ A, const bf16_t* __restrict__ Bt,
;                            bf16_t* __restrict__ Cb, float* __restrict__ Cf, const float* __restrict__ resid,
;                            float alpha) {
;     ...
;       for (int ai = 0; ai < 2; ++ai) {
;         int el = gtid;
;         asm volatile("" : "+v"(el));
;         const int ln = el & 63, rl0 = (el >> 6) * 16;
;         const unsigned goff = (unsigned)((brow + ai * HALF + rl0) * N + bcol + ln * 4);
;         float4 rr[16];
; #pragma unroll
;         for (int i = 0; i < 16; ++i) rr[i] = *(const float4*)(resid + (goff + (unsigned)(i * N)));
;         {
;           char* lb = cst + (((el >> 8) & 1) * 64 + (el & 15)) * FROW + (((el >> 6) & 3) * 32 + ((el >> 4) & 3) * 4) * 4;
;           for (int bj = 0; bj < 2; ++bj)
;             for (int m = 0; m < 4; ++m)
;               for (int n = 0; n < 2; ++n)
;                 *(f32x4*)(lb + m * 16 * FROW + bj * HALF * 4 + n * 64) = acc[ai][bj][m][n];
;         }
.LBB0_398:
	v_mov_b32_e32 v192, v150
	s_lshl_b32 s53, s54, 12
	s_add_i32 s52, s53, s52
	v_and_b32_e32 v242, 63, v192
	v_ashrrev_i32_e32 v243, 6, v192
	v_lshlrev_b32_e32 v132, 16, v243
	v_lshlrev_b32_e32 v142, 2, v242
	v_add3_u32 v132, v132, s52, v142
	v_add_u32_e32 v144, 0x2000, v132
	v_mov_b32_e32 v145, v133
	v_lshlrev_b64 v[202:203], 2, v[144:145]
	v_add_u32_e32 v144, 0x3000, v132
	v_lshlrev_b64 v[204:205], 2, v[144:145]
	v_add_u32_e32 v144, 0x4000, v132
	v_lshlrev_b64 v[206:207], 2, v[144:145]
	v_add_u32_e32 v144, 0x5000, v132
	v_lshlrev_b64 v[208:209], 2, v[144:145]
	v_add_u32_e32 v144, 0x6000, v132
	v_lshlrev_b64 v[210:211], 2, v[144:145]
	v_add_u32_e32 v144, 0x7000, v132
	v_add_u32_e32 v142, 0x1000, v132
	v_mov_b32_e32 v143, v133
	v_lshlrev_b64 v[212:213], 2, v[144:145]
	v_add_u32_e32 v144, 0x8000, v132
	v_lshlrev_b64 v[198:199], 2, v[132:133]
	v_lshlrev_b64 v[200:201], 2, v[142:143]
	v_lshlrev_b64 v[214:215], 2, v[144:145]
	v_add_u32_e32 v144, 0x9000, v132
	v_lshl_add_u64 v[146:147], s[14:15], 0, v[198:199]
	v_lshl_add_u64 v[142:143], s[14:15], 0, v[200:201]
	v_lshlrev_b64 v[216:217], 2, v[144:145]
	v_add_u32_e32 v144, 0xa000, v132
	v_lshlrev_b64 v[218:219], 2, v[144:145]
	global_load_dwordx4 v[142:145], v[142:143], off
	s_nop 0
	global_load_dwordx4 v[146:149], v[146:147], off
	v_add_u32_e32 v168, 0xb000, v132
	v_mov_b32_e32 v169, v133
	v_lshl_add_u64 v[170:171], s[14:15], 0, v[202:203]
	v_lshl_add_u64 v[166:167], s[14:15], 0, v[204:205]
	v_lshlrev_b64 v[222:223], 2, v[168:169]
	v_add_u32_e32 v168, 0xc000, v132
	v_lshlrev_b64 v[226:227], 2, v[168:169]
	global_load_dwordx4 v[166:169], v[166:167], off
	s_nop 0
	global_load_dwordx4 v[170:173], v[170:171], off
	v_lshl_add_u64 v[178:179], s[14:15], 0, v[206:207]
	v_lshl_add_u64 v[174:175], s[14:15], 0, v[208:209]
	v_add_u32_e32 v176, 0xd000, v132
	v_mov_b32_e32 v177, v133
	v_lshlrev_b64 v[230:231], 2, v[176:177]
	global_load_dwordx4 v[174:177], v[174:175], off
	s_nop 0
	global_load_dwordx4 v[178:181], v[178:179], off
	v_lshl_add_u64 v[186:187], s[14:15], 0, v[210:211]
	v_lshl_add_u64 v[182:183], s[14:15], 0, v[212:213]
	v_add_u32_e32 v184, 0xe000, v132
	v_mov_b32_e32 v185, v133
	v_lshlrev_b64 v[234:235], 2, v[184:185]
	global_load_dwordx4 v[182:185], v[182:183], off
	s_nop 0
	global_load_dwordx4 v[186:189], v[186:187], off
	v_add_u32_e32 v132, 0xf000, v132
	v_lshlrev_b64 v[238:239], 2, v[132:133]
	v_lshrrev_b32_e32 v132, 2, v192
	v_and_b32_e32 v193, 15, v192
	v_lshl_add_u64 v[194:195], s[14:15], 0, v[214:215]
	v_lshl_add_u64 v[190:191], s[14:15], 0, v[216:217]
	v_and_or_b32 v132, v132, 64, v193
	v_lshlrev_b32_e32 v193, 7, v243
	v_and_b32_e32 v244, 0x180, v193
	v_and_b32_e32 v245, 48, v192
	global_load_dwordx4 v[190:193], v[190:191], off
	s_nop 0
	global_load_dwordx4 v[194:197], v[194:195], off
	v_mad_u32_u24 v132, v132, s65, 16
	v_add3_u32 v132, v132, v244, v245
	v_lshl_add_u64 v[224:225], s[14:15], 0, v[222:223]
	ds_write_b128 v132, v[64:67]
	ds_write_b128 v132, v[68:71] offset:64
	ds_write_b128 v132, v[72:75] offset:16640
	ds_write_b128 v132, v[76:79] offset:16704
	ds_write_b128 v132, v[84:87] offset:33280
	v_lshl_add_u64 v[220:221], s[14:15], 0, v[218:219]
	global_load_dwordx4 v[64:67], v[224:225], off
	global_load_dwordx4 v[68:71], v[220:221], off
	v_lshl_add_u64 v[232:233], s[14:15], 0, v[230:231]
	ds_write_b128 v132, v[80:83] offset:33344
	ds_write_b128 v132, v[88:91] offset:49920
	ds_write_b128 v132, v[92:95] offset:49984
	ds_write_b128 v132, v[96:99] offset:512
	ds_write_b128 v132, v[100:103] offset:576
	ds_write_b128 v132, v[108:111] offset:17152
	v_lshl_add_u64 v[228:229], s[14:15], 0, v[226:227]
	global_load_dwordx4 v[72:75], v[232:233], off
	global_load_dwordx4 v[76:79], v[228:229], off
	v_lshl_add_u64 v[240:241], s[14:15], 0, v[238:239]
	ds_write_b128 v132, v[104:107] offset:17216
	ds_write_b128 v132, v[112:115] offset:33792
	ds_write_b128 v132, v[116:119] offset:33856
	ds_write_b128 v132, v[120:123] offset:50432
	ds_write_b128 v132, v[124:127] offset:50496
	v_lshl_add_u64 v[236:237], s[14:15], 0, v[234:235]
	global_load_dwordx4 v[80:83], v[240:241], off
	global_load_dwordx4 v[84:87], v[236:237], off
	v_mul_lo_u32 v88, v243, s66
	v_lshlrev_b32_e32 v89, 4, v242
	v_add3_u32 v132, 16, v88, v89
	s_waitcnt lgkmcnt(0)
	s_barrier
; #define WAIT_L(n) asm volatile("s_waitcnt lgkmcnt(" #n ")" ::: "memory")
; #define BAR __builtin_amdgcn_s_barrier()
; template <int MODE, int N>
; __device__ __forceinline__ void gemm_phase(const bf16_t* __restrict__ A, const bf16_t* __restrict__ Bt,
;                            bf16_t* __restrict__ Cb, float* __restrict__ Cf, const float* __restrict__ resid,
;                            float alpha) {
;     ...
;         WAIT_L(0);
;         BAR;
;         asm volatile("" ::: "memory");
;         {
;           const char* lptr = cst + rl0 * FROW + ln * 16;
; #pragma unroll
;           for (int i = 0; i < 16; ++i) {
;             f32x4 v = *(const f32x4*)(lptr + i * FROW);
;             float4 o;
;             o.x = alpha * rr[i].x + v[0]; o.y = alpha * rr[i].y + v[1]; o.z = alpha * rr[i].z + v[2]; o.w = alpha * rr[i].w + v[3];
;             *(float4*)(Cf + (goff + (unsigned)(i * N))) = o;
;           }
;         }
;         WAIT_L(0);
;         BAR;
;         asm volatile("" ::: "memory");
	ds_read_b128 v[88:91], v132
	ds_read_b128 v[92:95], v132 offset:1040
	v_lshl_add_u64 v[96:97], s[12:13], 0, v[198:199]
	v_lshl_add_u64 v[98:99], s[12:13], 0, v[200:201]
	v_lshl_add_u64 v[100:101], s[12:13], 0, v[202:203]
	v_lshl_add_u64 v[102:103], s[12:13], 0, v[204:205]
	v_lshl_add_u64 v[104:105], s[12:13], 0, v[206:207]
	v_lshl_add_u64 v[106:107], s[12:13], 0, v[208:209]
	v_lshl_add_u64 v[108:109], s[12:13], 0, v[210:211]
	v_lshl_add_u64 v[110:111], s[12:13], 0, v[212:213]
	v_lshl_add_u64 v[112:113], s[12:13], 0, v[214:215]
	v_lshl_add_u64 v[114:115], s[12:13], 0, v[216:217]
	v_lshl_add_u64 v[116:117], s[12:13], 0, v[218:219]
	v_lshl_add_u64 v[118:119], s[12:13], 0, v[222:223]
	v_lshl_add_u64 v[120:121], s[12:13], 0, v[226:227]
	v_lshl_add_u64 v[122:123], s[12:13], 0, v[230:231]
	v_lshl_add_u64 v[124:125], s[12:13], 0, v[234:235]
	v_lshl_add_u64 v[126:127], s[12:13], 0, v[238:239]
	s_add_i32 s52, s52, 0x80000
	s_add_i32 s67, s67, s68
	s_cmpk_gt_i32 s67, 0x1ff
	s_cselect_b64 s[56:57], -1, 0
	s_and_b64 vcc, exec, s[56:57]
	s_mov_b32 s54, 0
	s_waitcnt vmcnt(15) lgkmcnt(0)
	v_pk_fma_f32 v[92:93], v[142:143], s[50:51], v[92:93] op_sel_hi:[1,0,1]
	s_waitcnt vmcnt(14)
	v_pk_fma_f32 v[88:89], v[146:147], s[50:51], v[88:89] op_sel_hi:[1,0,1]
	v_pk_fma_f32 v[90:91], v[148:149], s[50:51], v[90:91] op_sel_hi:[1,0,1]
	global_store_dwordx4 v[96:97], v[88:91], off
	ds_read_b128 v[88:91], v132 offset:2080
	v_pk_fma_f32 v[94:95], v[144:145], s[50:51], v[94:95] op_sel_hi:[1,0,1]
	global_store_dwordx4 v[98:99], v[92:95], off
	ds_read_b128 v[92:95], v132 offset:3120
	v_mov_b32_e32 v98, v150
	s_waitcnt vmcnt(14) lgkmcnt(1)
	v_pk_fma_f32 v[88:89], v[170:171], s[50:51], v[88:89] op_sel_hi:[1,0,1]
	v_pk_fma_f32 v[90:91], v[172:173], s[50:51], v[90:91] op_sel_hi:[1,0,1]
	global_store_dwordx4 v[100:101], v[88:91], off
	ds_read_b128 v[88:91], v132 offset:4160
	s_waitcnt lgkmcnt(1)
	v_pk_fma_f32 v[92:93], v[166:167], s[50:51], v[92:93] op_sel_hi:[1,0,1]
	v_pk_fma_f32 v[94:95], v[168:169], s[50:51], v[94:95] op_sel_hi:[1,0,1]
	global_store_dwordx4 v[102:103], v[92:95], off
	ds_read_b128 v[92:95], v132 offset:5200
	s_waitcnt vmcnt(14) lgkmcnt(1)
	v_pk_fma_f32 v[88:89], v[178:179], s[50:51], v[88:89] op_sel_hi:[1,0,1]
	v_pk_fma_f32 v[90:91], v[180:181], s[50:51], v[90:91] op_sel_hi:[1,0,1]
	global_store_dwordx4 v[104:105], v[88:91], off
	ds_read_b128 v[88:91], v132 offset:6240
	s_waitcnt lgkmcnt(1)
	v_pk_fma_f32 v[92:93], v[174:175], s[50:51], v[92:93] op_sel_hi:[1,0,1]
	v_pk_fma_f32 v[94:95], v[176:177], s[50:51], v[94:95] op_sel_hi:[1,0,1]
	global_store_dwordx4 v[106:107], v[92:95], off
	ds_read_b128 v[92:95], v132 offset:7280
	s_waitcnt vmcnt(14) lgkmcnt(1)
	v_pk_fma_f32 v[88:89], v[186:187], s[50:51], v[88:89] op_sel_hi:[1,0,1]
	v_pk_fma_f32 v[90:91], v[188:189], s[50:51], v[90:91] op_sel_hi:[1,0,1]
	global_store_dwordx4 v[108:109], v[88:91], off
	ds_read_b128 v[88:91], v132 offset:8320
	s_waitcnt lgkmcnt(1)
	v_pk_fma_f32 v[92:93], v[182:183], s[50:51], v[92:93] op_sel_hi:[1,0,1]
	v_pk_fma_f32 v[94:95], v[184:185], s[50:51], v[94:95] op_sel_hi:[1,0,1]
	global_store_dwordx4 v[110:111], v[92:95], off
	ds_read_b128 v[92:95], v132 offset:9360
	s_waitcnt vmcnt(14) lgkmcnt(1)
	v_pk_fma_f32 v[88:89], v[194:195], s[50:51], v[88:89] op_sel_hi:[1,0,1]
	v_pk_fma_f32 v[90:91], v[196:197], s[50:51], v[90:91] op_sel_hi:[1,0,1]
	global_store_dwordx4 v[112:113], v[88:91], off
	ds_read_b128 v[88:91], v132 offset:10400
	s_waitcnt lgkmcnt(1)
	v_pk_fma_f32 v[92:93], v[190:191], s[50:51], v[92:93] op_sel_hi:[1,0,1]
	v_pk_fma_f32 v[94:95], v[192:193], s[50:51], v[94:95] op_sel_hi:[1,0,1]
	global_store_dwordx4 v[114:115], v[92:95], off
	ds_read_b128 v[92:95], v132 offset:11440
	s_waitcnt vmcnt(14) lgkmcnt(1)
	v_pk_fma_f32 v[68:69], v[68:69], s[50:51], v[88:89] op_sel_hi:[1,0,1]
	v_pk_fma_f32 v[70:71], v[70:71], s[50:51], v[90:91] op_sel_hi:[1,0,1]
	global_store_dwordx4 v[116:117], v[68:71], off
	ds_read_b128 v[68:71], v132 offset:12480
	s_waitcnt lgkmcnt(1)
	v_pk_fma_f32 v[64:65], v[64:65], s[50:51], v[92:93] op_sel_hi:[1,0,1]
	v_pk_fma_f32 v[66:67], v[66:67], s[50:51], v[94:95] op_sel_hi:[1,0,1]
	global_store_dwordx4 v[118:119], v[64:67], off
	ds_read_b128 v[64:67], v132 offset:13520
	s_waitcnt vmcnt(14) lgkmcnt(1)
	v_pk_fma_f32 v[68:69], v[76:77], s[50:51], v[68:69] op_sel_hi:[1,0,1]
	v_pk_fma_f32 v[70:71], v[78:79], s[50:51], v[70:71] op_sel_hi:[1,0,1]
	global_store_dwordx4 v[120:121], v[68:71], off
	ds_read_b128 v[68:71], v132 offset:14560
	s_waitcnt lgkmcnt(1)
	v_pk_fma_f32 v[64:65], v[72:73], s[50:51], v[64:65] op_sel_hi:[1,0,1]
	v_pk_fma_f32 v[66:67], v[74:75], s[50:51], v[66:67] op_sel_hi:[1,0,1]
	ds_read_b128 v[72:75], v132 offset:15600
	global_store_dwordx4 v[122:123], v[64:67], off
	v_mov_b32_e32 v91, v133
	s_waitcnt vmcnt(14) lgkmcnt(1)
	v_pk_fma_f32 v[64:65], v[84:85], s[50:51], v[68:69] op_sel_hi:[1,0,1]
	v_pk_fma_f32 v[66:67], v[86:87], s[50:51], v[70:71] op_sel_hi:[1,0,1]
	global_store_dwordx4 v[124:125], v[64:67], off
	s_waitcnt lgkmcnt(0)
	s_nop 0
	v_pk_fma_f32 v[64:65], v[80:81], s[50:51], v[72:73] op_sel_hi:[1,0,1]
	v_pk_fma_f32 v[66:67], v[82:83], s[50:51], v[74:75] op_sel_hi:[1,0,1]
	global_store_dwordx4 v[126:127], v[64:67], off
	s_waitcnt lgkmcnt(0)
	s_barrier
; template <int MODE, int N>
; __device__ __forceinline__ void gemm_phase(const bf16_t* __restrict__ A, const bf16_t* __restrict__ Bt,
;                            bf16_t* __restrict__ Cb, float* __restrict__ Cf, const float* __restrict__ resid,
;                            float alpha) {
;     ...
;       for (int ai = 0; ai < 2; ++ai) {
;         int el = gtid;
;         asm volatile("" : "+v"(el));
;         const int ln = el & 63, rl0 = (el >> 6) * 16;
;         const unsigned goff = (unsigned)((brow + ai * HALF + rl0) * N + bcol + ln * 4);
;         float4 rr[16];
; #pragma unroll
;         for (int i = 0; i < 16; ++i) rr[i] = *(const float4*)(resid + (goff + (unsigned)(i * N)));
;         {
;           char* lb = cst + (((el >> 8) & 1) * 64 + (el & 15)) * FROW + (((el >> 6) & 3) * 32 + ((el >> 4) & 3) * 4) * 4;
;           for (int bj = 0; bj < 2; ++bj)
;             for (int m = 0; m < 4; ++m)
;               for (int n = 0; n < 2; ++n)
;                 *(f32x4*)(lb + m * 16 * FROW + bj * HALF * 4 + n * 64) = acc[ai][bj][m][n];
;         }
	v_mov_b32_e32 v75, v133
	v_and_b32_e32 v178, 63, v98
	v_ashrrev_i32_e32 v179, 6, v98
	v_lshlrev_b32_e32 v64, 16, v179
	v_lshlrev_b32_e32 v65, 2, v178
	v_add3_u32 v132, s52, v64, v65
	v_add_u32_e32 v66, 0x2000, v132
	v_mov_b32_e32 v67, v133
	v_lshlrev_b64 v[108:109], 2, v[66:67]
	v_add_u32_e32 v66, 0x3000, v132
	v_lshlrev_b64 v[110:111], 2, v[66:67]
	v_add_u32_e32 v66, 0x4000, v132
	v_lshlrev_b64 v[112:113], 2, v[66:67]
	v_add_u32_e32 v66, 0x5000, v132
	v_lshlrev_b64 v[114:115], 2, v[66:67]
	v_add_u32_e32 v66, 0x6000, v132
	v_lshlrev_b64 v[116:117], 2, v[66:67]
	v_add_u32_e32 v66, 0x7000, v132
	v_add_u32_e32 v64, 0x1000, v132
	v_mov_b32_e32 v65, v133
	v_lshlrev_b64 v[118:119], 2, v[66:67]
	v_add_u32_e32 v66, 0x8000, v132
	v_lshlrev_b64 v[104:105], 2, v[132:133]
	v_lshlrev_b64 v[106:107], 2, v[64:65]
	v_lshlrev_b64 v[120:121], 2, v[66:67]
	v_add_u32_e32 v66, 0x9000, v132
	v_lshl_add_u64 v[68:69], s[14:15], 0, v[104:105]
	v_lshl_add_u64 v[64:65], s[14:15], 0, v[106:107]
	v_lshlrev_b64 v[122:123], 2, v[66:67]
	v_add_u32_e32 v66, 0xa000, v132
	v_lshlrev_b64 v[124:125], 2, v[66:67]
	global_load_dwordx4 v[64:67], v[64:65], off
	s_nop 0
	global_load_dwordx4 v[68:71], v[68:69], off
	v_add_u32_e32 v74, 0xb000, v132
	v_lshl_add_u64 v[76:77], s[14:15], 0, v[108:109]
	v_lshl_add_u64 v[72:73], s[14:15], 0, v[110:111]
	v_lshlrev_b64 v[142:143], 2, v[74:75]
	v_add_u32_e32 v74, 0xc000, v132
	v_lshlrev_b64 v[146:147], 2, v[74:75]
	global_load_dwordx4 v[72:75], v[72:73], off
	s_nop 0
	global_load_dwordx4 v[76:79], v[76:77], off
	v_lshl_add_u64 v[84:85], s[14:15], 0, v[112:113]
	v_lshl_add_u64 v[80:81], s[14:15], 0, v[114:115]
	v_add_u32_e32 v82, 0xd000, v132
	v_mov_b32_e32 v83, v133
	v_lshlrev_b64 v[166:167], 2, v[82:83]
	global_load_dwordx4 v[80:83], v[80:81], off
	s_nop 0
	global_load_dwordx4 v[84:87], v[84:85], off
	v_lshl_add_u64 v[92:93], s[14:15], 0, v[116:117]
	v_lshl_add_u64 v[88:89], s[14:15], 0, v[118:119]
	v_add_u32_e32 v90, 0xe000, v132
	v_lshlrev_b64 v[170:171], 2, v[90:91]
	global_load_dwordx4 v[88:91], v[88:89], off
	s_nop 0
	global_load_dwordx4 v[92:95], v[92:93], off
	v_lshrrev_b32_e32 v99, 2, v98
	v_and_b32_e32 v102, 15, v98
	v_add_u32_e32 v132, 0xf000, v132
	v_and_or_b32 v99, v99, 64, v102
	v_lshl_add_u64 v[100:101], s[14:15], 0, v[120:121]
	v_lshl_add_u64 v[96:97], s[14:15], 0, v[122:123]
	v_lshlrev_b64 v[174:175], 2, v[132:133]
	v_mad_u32_u24 v132, v99, s65, 16
	v_lshlrev_b32_e32 v99, 7, v179
	v_and_b32_e32 v180, 0x180, v99
	v_and_b32_e32 v181, 48, v98
	global_load_dwordx4 v[96:99], v[96:97], off
	s_nop 0
	global_load_dwordx4 v[100:103], v[100:101], off
	v_add3_u32 v132, v132, v180, v181
	v_lshl_add_u64 v[144:145], s[14:15], 0, v[142:143]
	ds_write_b128 v132, v[0:3]
	ds_write_b128 v132, v[4:7] offset:64
	ds_write_b128 v132, v[8:11] offset:16640
	ds_write_b128 v132, v[12:15] offset:16704
	ds_write_b128 v132, v[20:23] offset:33280
	v_lshl_add_u64 v[126:127], s[14:15], 0, v[124:125]
	global_load_dwordx4 v[0:3], v[144:145], off
	global_load_dwordx4 v[4:7], v[126:127], off
	v_lshl_add_u64 v[168:169], s[14:15], 0, v[166:167]
	ds_write_b128 v132, v[16:19] offset:33344
	ds_write_b128 v132, v[24:27] offset:49920
	ds_write_b128 v132, v[28:31] offset:49984
	ds_write_b128 v132, v[32:35] offset:512
	ds_write_b128 v132, v[36:39] offset:576
	ds_write_b128 v132, v[44:47] offset:17152
	v_lshl_add_u64 v[148:149], s[14:15], 0, v[146:147]
	global_load_dwordx4 v[8:11], v[168:169], off
	global_load_dwordx4 v[12:15], v[148:149], off
	v_lshl_add_u64 v[176:177], s[14:15], 0, v[174:175]
	ds_write_b128 v132, v[40:43] offset:17216
	ds_write_b128 v132, v[48:51] offset:33792
	ds_write_b128 v132, v[52:55] offset:33856
	ds_write_b128 v132, v[56:59] offset:50432
	ds_write_b128 v132, v[60:63] offset:50496
	v_lshl_add_u64 v[172:173], s[14:15], 0, v[170:171]
	global_load_dwordx4 v[16:19], v[176:177], off
	global_load_dwordx4 v[20:23], v[172:173], off
	v_mul_lo_u32 v24, v179, s66
	v_lshlrev_b32_e32 v25, 4, v178
	v_add3_u32 v126, 16, v24, v25
	s_waitcnt lgkmcnt(0)
	s_barrier
; #define WAIT_L(n) asm volatile("s_waitcnt lgkmcnt(" #n ")" ::: "memory")
; #define BAR __builtin_amdgcn_s_barrier()
; template <int MODE, int N>
; __device__ __forceinline__ void gemm_phase(const bf16_t* __restrict__ A, const bf16_t* __restrict__ Bt,
;                            bf16_t* __restrict__ Cb, float* __restrict__ Cf, const float* __restrict__ resid,
;                            float alpha) {
;     ...
;         WAIT_L(0);
;         BAR;
;         asm volatile("" ::: "memory");
;         {
;           const char* lptr = cst + rl0 * FROW + ln * 16;
; #pragma unroll
;           for (int i = 0; i < 16; ++i) {
;             f32x4 v = *(const f32x4*)(lptr + i * FROW);
;             float4 o;
;             o.x = alpha * rr[i].x + v[0]; o.y = alpha * rr[i].y + v[1]; o.z = alpha * rr[i].z + v[2]; o.w = alpha * rr[i].w + v[3];
;             *(float4*)(Cf + (goff + (unsigned)(i * N))) = o;
;           }
;         }
;         WAIT_L(0);
;         BAR;
;         asm volatile("" ::: "memory");
;       }
;       if (tile + (int)gridDim.x < nwg) {
;         TILE_COORDS(tile + (int)gridDim.x, nbrow, nbcol);
;         PROLOGUE_ISSUE(nbrow, nbcol);
;       }
	ds_read_b128 v[24:27], v126
	ds_read_b128 v[28:31], v126 offset:1040
	v_lshl_add_u64 v[32:33], s[12:13], 0, v[104:105]
	v_lshl_add_u64 v[34:35], s[12:13], 0, v[106:107]
	v_lshl_add_u64 v[36:37], s[12:13], 0, v[108:109]
	v_lshl_add_u64 v[38:39], s[12:13], 0, v[110:111]
	v_lshl_add_u64 v[40:41], s[12:13], 0, v[112:113]
	v_lshl_add_u64 v[42:43], s[12:13], 0, v[114:115]
	v_lshl_add_u64 v[44:45], s[12:13], 0, v[116:117]
	v_lshl_add_u64 v[46:47], s[12:13], 0, v[118:119]
	v_lshl_add_u64 v[48:49], s[12:13], 0, v[120:121]
	v_lshl_add_u64 v[50:51], s[12:13], 0, v[122:123]
	v_lshl_add_u64 v[52:53], s[12:13], 0, v[124:125]
	v_lshl_add_u64 v[54:55], s[12:13], 0, v[142:143]
	v_lshl_add_u64 v[56:57], s[12:13], 0, v[146:147]
	v_lshl_add_u64 v[58:59], s[12:13], 0, v[166:167]
	v_lshl_add_u64 v[60:61], s[12:13], 0, v[170:171]
	v_lshl_add_u64 v[62:63], s[12:13], 0, v[174:175]
	s_mov_b32 s52, 0
	s_waitcnt vmcnt(15) lgkmcnt(0)
	v_pk_fma_f32 v[28:29], v[64:65], s[50:51], v[28:29] op_sel_hi:[1,0,1]
	s_waitcnt vmcnt(14)
	v_pk_fma_f32 v[24:25], v[68:69], s[50:51], v[24:25] op_sel_hi:[1,0,1]
	v_pk_fma_f32 v[26:27], v[70:71], s[50:51], v[26:27] op_sel_hi:[1,0,1]
	global_store_dwordx4 v[32:33], v[24:27], off
	ds_read_b128 v[24:27], v126 offset:2080
	v_pk_fma_f32 v[30:31], v[66:67], s[50:51], v[30:31] op_sel_hi:[1,0,1]
	global_store_dwordx4 v[34:35], v[28:31], off
	ds_read_b128 v[28:31], v126 offset:3120
	s_waitcnt vmcnt(14) lgkmcnt(1)
	v_pk_fma_f32 v[24:25], v[76:77], s[50:51], v[24:25] op_sel_hi:[1,0,1]
	v_pk_fma_f32 v[26:27], v[78:79], s[50:51], v[26:27] op_sel_hi:[1,0,1]
	global_store_dwordx4 v[36:37], v[24:27], off
	ds_read_b128 v[24:27], v126 offset:4160
	s_waitcnt lgkmcnt(1)
	v_pk_fma_f32 v[28:29], v[72:73], s[50:51], v[28:29] op_sel_hi:[1,0,1]
	v_pk_fma_f32 v[30:31], v[74:75], s[50:51], v[30:31] op_sel_hi:[1,0,1]
	global_store_dwordx4 v[38:39], v[28:31], off
	ds_read_b128 v[28:31], v126 offset:5200
	s_waitcnt vmcnt(14) lgkmcnt(1)
	v_pk_fma_f32 v[24:25], v[84:85], s[50:51], v[24:25] op_sel_hi:[1,0,1]
	v_pk_fma_f32 v[26:27], v[86:87], s[50:51], v[26:27] op_sel_hi:[1,0,1]
	global_store_dwordx4 v[40:41], v[24:27], off
	ds_read_b128 v[24:27], v126 offset:6240
	s_waitcnt lgkmcnt(1)
	v_pk_fma_f32 v[28:29], v[80:81], s[50:51], v[28:29] op_sel_hi:[1,0,1]
	v_pk_fma_f32 v[30:31], v[82:83], s[50:51], v[30:31] op_sel_hi:[1,0,1]
	global_store_dwordx4 v[42:43], v[28:31], off
	ds_read_b128 v[28:31], v126 offset:7280
	s_waitcnt vmcnt(14) lgkmcnt(1)
	v_pk_fma_f32 v[24:25], v[92:93], s[50:51], v[24:25] op_sel_hi:[1,0,1]
	v_pk_fma_f32 v[26:27], v[94:95], s[50:51], v[26:27] op_sel_hi:[1,0,1]
	global_store_dwordx4 v[44:45], v[24:27], off
	ds_read_b128 v[24:27], v126 offset:8320
	s_waitcnt lgkmcnt(1)
	v_pk_fma_f32 v[28:29], v[88:89], s[50:51], v[28:29] op_sel_hi:[1,0,1]
	v_pk_fma_f32 v[30:31], v[90:91], s[50:51], v[30:31] op_sel_hi:[1,0,1]
	global_store_dwordx4 v[46:47], v[28:31], off
	ds_read_b128 v[28:31], v126 offset:9360
	s_waitcnt vmcnt(14) lgkmcnt(1)
	v_pk_fma_f32 v[24:25], v[100:101], s[50:51], v[24:25] op_sel_hi:[1,0,1]
	v_pk_fma_f32 v[26:27], v[102:103], s[50:51], v[26:27] op_sel_hi:[1,0,1]
	global_store_dwordx4 v[48:49], v[24:27], off
	ds_read_b128 v[24:27], v126 offset:10400
	s_waitcnt lgkmcnt(1)
	v_pk_fma_f32 v[28:29], v[96:97], s[50:51], v[28:29] op_sel_hi:[1,0,1]
	v_pk_fma_f32 v[30:31], v[98:99], s[50:51], v[30:31] op_sel_hi:[1,0,1]
	global_store_dwordx4 v[50:51], v[28:31], off
	ds_read_b128 v[28:31], v126 offset:11440
	s_waitcnt vmcnt(14) lgkmcnt(1)
	v_pk_fma_f32 v[4:5], v[4:5], s[50:51], v[24:25] op_sel_hi:[1,0,1]
	v_pk_fma_f32 v[6:7], v[6:7], s[50:51], v[26:27] op_sel_hi:[1,0,1]
	global_store_dwordx4 v[52:53], v[4:7], off
	ds_read_b128 v[4:7], v126 offset:12480
	s_waitcnt lgkmcnt(1)
	v_pk_fma_f32 v[0:1], v[0:1], s[50:51], v[28:29] op_sel_hi:[1,0,1]
	v_pk_fma_f32 v[2:3], v[2:3], s[50:51], v[30:31] op_sel_hi:[1,0,1]
	global_store_dwordx4 v[54:55], v[0:3], off
	ds_read_b128 v[0:3], v126 offset:13520
	s_waitcnt vmcnt(14) lgkmcnt(1)
	v_pk_fma_f32 v[4:5], v[12:13], s[50:51], v[4:5] op_sel_hi:[1,0,1]
	v_pk_fma_f32 v[6:7], v[14:15], s[50:51], v[6:7] op_sel_hi:[1,0,1]
	global_store_dwordx4 v[56:57], v[4:7], off
	ds_read_b128 v[4:7], v126 offset:14560
	s_waitcnt lgkmcnt(1)
	v_pk_fma_f32 v[0:1], v[8:9], s[50:51], v[0:1] op_sel_hi:[1,0,1]
	v_pk_fma_f32 v[2:3], v[10:11], s[50:51], v[2:3] op_sel_hi:[1,0,1]
	ds_read_b128 v[8:11], v126 offset:15600
	global_store_dwordx4 v[58:59], v[0:3], off
	s_waitcnt vmcnt(14) lgkmcnt(1)
	s_nop 0
	v_pk_fma_f32 v[0:1], v[20:21], s[50:51], v[4:5] op_sel_hi:[1,0,1]
	v_pk_fma_f32 v[2:3], v[22:23], s[50:51], v[6:7] op_sel_hi:[1,0,1]
	global_store_dwordx4 v[60:61], v[0:3], off
	s_waitcnt lgkmcnt(0)
	s_nop 0
	v_pk_fma_f32 v[0:1], v[16:17], s[50:51], v[8:9] op_sel_hi:[1,0,1]
	v_pk_fma_f32 v[2:3], v[18:19], s[50:51], v[10:11] op_sel_hi:[1,0,1]
	global_store_dwordx4 v[62:63], v[0:3], off
	s_waitcnt lgkmcnt(0)
	s_barrier
	s_cbranch_vccnz .LBB0_391
	s_ashr_i32 s52, s67, 31
	s_lshr_b32 s52, s52, 29
	s_add_i32 s54, s67, s52
	s_and_b32 s52, s54, -8
	s_sub_i32 s69, s67, s52
	s_cmp_gt_i32 s69, -1
	s_mov_b64 s[52:53], -1
	s_cbranch_scc0 .LBB0_401
	s_lshl_b32 s55, s69, 6
	s_mov_b64 s[52:53], 0

; template <int MODE, int N>
; __device__ __forceinline__ void gemm_phase(const bf16_t* __restrict__ A, const bf16_t* __restrict__ Bt,
;                            bf16_t* __restrict__ Cb, float* __restrict__ Cf, const float* __restrict__ resid,
;                            float alpha) {
;     ...
;       for (int ai = 0; ai < 2; ++ai) {
;         int el = gtid;
;         asm volatile("" : "+v"(el));
;         const int ln = el & 63, rl0 = (el >> 6) * 16;
;         const unsigned goff = (unsigned)((brow + ai * HALF + rl0) * N + bcol + ln * 4);
;         float4 rr[16];
; #pragma unroll
;         for (int i = 0; i < 16; ++i) rr[i] = *(const float4*)(resid + (goff + (unsigned)(i * N)));
;         {
;           char* lb = cst + (((el >> 8) & 1) * 64 + (el & 15)) * FROW + (((el >> 6) & 3) * 32 + ((el >> 4) & 3) * 4) * 4;
;           for (int bj = 0; bj < 2; ++bj)
;             for (int m = 0; m < 4; ++m)
;               for (int n = 0; n < 2; ++n)
;                 *(f32x4*)(lb + m * 16 * FROW + bj * HALF * 4 + n * 64) = acc[ai][bj][m][n];
;         }
.LBB0_734:
	v_mov_b32_e32 v192, v150
	s_lshl_b32 s45, s46, 12
	s_add_i32 s44, s45, s44
	v_and_b32_e32 v242, 63, v192
	v_ashrrev_i32_e32 v243, 6, v192
	v_lshlrev_b32_e32 v132, 16, v243
	v_lshlrev_b32_e32 v142, 2, v242
	v_add3_u32 v132, v132, s44, v142
	v_add_u32_e32 v144, 0x2000, v132
	v_mov_b32_e32 v145, v133
	v_lshlrev_b64 v[202:203], 2, v[144:145]
	v_add_u32_e32 v144, 0x3000, v132
	v_lshlrev_b64 v[204:205], 2, v[144:145]
	v_add_u32_e32 v144, 0x4000, v132
	v_lshlrev_b64 v[206:207], 2, v[144:145]
	v_add_u32_e32 v144, 0x5000, v132
	v_lshlrev_b64 v[208:209], 2, v[144:145]
	v_add_u32_e32 v144, 0x6000, v132
	v_lshlrev_b64 v[210:211], 2, v[144:145]
	v_add_u32_e32 v144, 0x7000, v132
	v_add_u32_e32 v142, 0x1000, v132
	v_mov_b32_e32 v143, v133
	v_lshlrev_b64 v[212:213], 2, v[144:145]
	v_add_u32_e32 v144, 0x8000, v132
	v_lshlrev_b64 v[198:199], 2, v[132:133]
	v_lshlrev_b64 v[200:201], 2, v[142:143]
	v_lshlrev_b64 v[214:215], 2, v[144:145]
	v_add_u32_e32 v144, 0x9000, v132
	v_lshl_add_u64 v[146:147], s[10:11], 0, v[198:199]
	v_lshl_add_u64 v[142:143], s[10:11], 0, v[200:201]
	v_lshlrev_b64 v[216:217], 2, v[144:145]
	v_add_u32_e32 v144, 0xa000, v132
	v_lshlrev_b64 v[218:219], 2, v[144:145]
	global_load_dwordx4 v[142:145], v[142:143], off
	s_nop 0
	global_load_dwordx4 v[146:149], v[146:147], off
	v_add_u32_e32 v168, 0xb000, v132
	v_mov_b32_e32 v169, v133
	v_lshl_add_u64 v[170:171], s[10:11], 0, v[202:203]
	v_lshl_add_u64 v[166:167], s[10:11], 0, v[204:205]
	v_lshlrev_b64 v[222:223], 2, v[168:169]
	v_add_u32_e32 v168, 0xc000, v132
	v_lshlrev_b64 v[226:227], 2, v[168:169]
	global_load_dwordx4 v[166:169], v[166:167], off
	s_nop 0
	global_load_dwordx4 v[170:173], v[170:171], off
	v_lshl_add_u64 v[178:179], s[10:11], 0, v[206:207]
	v_lshl_add_u64 v[174:175], s[10:11], 0, v[208:209]
	v_add_u32_e32 v176, 0xd000, v132
	v_mov_b32_e32 v177, v133
	v_lshlrev_b64 v[230:231], 2, v[176:177]
	global_load_dwordx4 v[174:177], v[174:175], off
	s_nop 0
	global_load_dwordx4 v[178:181], v[178:179], off
	v_lshl_add_u64 v[186:187], s[10:11], 0, v[210:211]
	v_lshl_add_u64 v[182:183], s[10:11], 0, v[212:213]
	v_add_u32_e32 v184, 0xe000, v132
	v_mov_b32_e32 v185, v133
	v_lshlrev_b64 v[234:235], 2, v[184:185]
	global_load_dwordx4 v[182:185], v[182:183], off
	s_nop 0
	global_load_dwordx4 v[186:189], v[186:187], off
	v_add_u32_e32 v132, 0xf000, v132
	v_lshlrev_b64 v[238:239], 2, v[132:133]
	v_lshrrev_b32_e32 v132, 2, v192
	v_and_b32_e32 v193, 15, v192
	v_lshl_add_u64 v[194:195], s[10:11], 0, v[214:215]
	v_lshl_add_u64 v[190:191], s[10:11], 0, v[216:217]
	v_and_or_b32 v132, v132, 64, v193
	v_lshlrev_b32_e32 v193, 7, v243
	v_and_b32_e32 v244, 0x180, v193
	v_and_b32_e32 v245, 48, v192
	global_load_dwordx4 v[190:193], v[190:191], off
	s_nop 0
	global_load_dwordx4 v[194:197], v[194:195], off
	v_mad_u32_u24 v132, v132, s59, 16
	v_add3_u32 v132, v132, v244, v245
	v_lshl_add_u64 v[224:225], s[10:11], 0, v[222:223]
	ds_write_b128 v132, v[64:67]
	ds_write_b128 v132, v[68:71] offset:64
	ds_write_b128 v132, v[72:75] offset:16640
	ds_write_b128 v132, v[76:79] offset:16704
	ds_write_b128 v132, v[84:87] offset:33280
	v_lshl_add_u64 v[220:221], s[10:11], 0, v[218:219]
	global_load_dwordx4 v[64:67], v[224:225], off
	global_load_dwordx4 v[68:71], v[220:221], off
	v_lshl_add_u64 v[232:233], s[10:11], 0, v[230:231]
	ds_write_b128 v132, v[80:83] offset:33344
	ds_write_b128 v132, v[88:91] offset:49920
	ds_write_b128 v132, v[92:95] offset:49984
	ds_write_b128 v132, v[96:99] offset:512
	ds_write_b128 v132, v[100:103] offset:576
	ds_write_b128 v132, v[108:111] offset:17152
	v_lshl_add_u64 v[228:229], s[10:11], 0, v[226:227]
	global_load_dwordx4 v[72:75], v[232:233], off
	global_load_dwordx4 v[76:79], v[228:229], off
	v_lshl_add_u64 v[240:241], s[10:11], 0, v[238:239]
	ds_write_b128 v132, v[104:107] offset:17216
	ds_write_b128 v132, v[112:115] offset:33792
	ds_write_b128 v132, v[116:119] offset:33856
	ds_write_b128 v132, v[120:123] offset:50432
	ds_write_b128 v132, v[124:127] offset:50496
	v_lshl_add_u64 v[236:237], s[10:11], 0, v[234:235]
	global_load_dwordx4 v[80:83], v[240:241], off
	global_load_dwordx4 v[84:87], v[236:237], off
	v_mul_lo_u32 v88, v243, s60
	v_lshlrev_b32_e32 v89, 4, v242
	v_add3_u32 v132, 16, v88, v89
	s_waitcnt lgkmcnt(0)
	s_barrier
; #define WAIT_L(n) asm volatile("s_waitcnt lgkmcnt(" #n ")" ::: "memory")
; #define BAR __builtin_amdgcn_s_barrier()
; template <int MODE, int N>
; __device__ __forceinline__ void gemm_phase(const bf16_t* __restrict__ A, const bf16_t* __restrict__ Bt,
;                            bf16_t* __restrict__ Cb, float* __restrict__ Cf, const float* __restrict__ resid,
;                            float alpha) {
;     ...
;         WAIT_L(0);
;         BAR;
;         asm volatile("" ::: "memory");
;         {
;           const char* lptr = cst + rl0 * FROW + ln * 16;
; #pragma unroll
;           for (int i = 0; i < 16; ++i) {
;             f32x4 v = *(const f32x4*)(lptr + i * FROW);
;             float4 o;
;             o.x = alpha * rr[i].x + v[0]; o.y = alpha * rr[i].y + v[1]; o.z = alpha * rr[i].z + v[2]; o.w = alpha * rr[i].w + v[3];
;             *(float4*)(Cf + (goff + (unsigned)(i * N))) = o;
;           }
;         }
;         WAIT_L(0);
;         BAR;
;         asm volatile("" ::: "memory");
	ds_read_b128 v[88:91], v132
	ds_read_b128 v[92:95], v132 offset:1040
	v_lshl_add_u64 v[96:97], s[8:9], 0, v[198:199]
	v_lshl_add_u64 v[98:99], s[8:9], 0, v[200:201]
	v_lshl_add_u64 v[100:101], s[8:9], 0, v[202:203]
	v_lshl_add_u64 v[102:103], s[8:9], 0, v[204:205]
	v_lshl_add_u64 v[104:105], s[8:9], 0, v[206:207]
	v_lshl_add_u64 v[106:107], s[8:9], 0, v[208:209]
	v_lshl_add_u64 v[108:109], s[8:9], 0, v[210:211]
	v_lshl_add_u64 v[110:111], s[8:9], 0, v[212:213]
	v_lshl_add_u64 v[112:113], s[8:9], 0, v[214:215]
	v_lshl_add_u64 v[114:115], s[8:9], 0, v[216:217]
	v_lshl_add_u64 v[116:117], s[8:9], 0, v[218:219]
	v_lshl_add_u64 v[118:119], s[8:9], 0, v[222:223]
	v_lshl_add_u64 v[120:121], s[8:9], 0, v[226:227]
	v_lshl_add_u64 v[122:123], s[8:9], 0, v[230:231]
	v_lshl_add_u64 v[124:125], s[8:9], 0, v[234:235]
	v_lshl_add_u64 v[126:127], s[8:9], 0, v[238:239]
	s_add_i32 s44, s44, 0x80000
	s_add_i32 s2, s2, s18
	s_cmpk_gt_i32 s2, 0x1ff
	s_cselect_b64 s[48:49], -1, 0
	s_and_b64 vcc, exec, s[48:49]
	s_mov_b32 s46, 0
	s_waitcnt vmcnt(15) lgkmcnt(0)
	v_pk_fma_f32 v[92:93], v[142:143], s[42:43], v[92:93] op_sel_hi:[1,0,1]
	s_waitcnt vmcnt(14)
	v_pk_fma_f32 v[88:89], v[146:147], s[42:43], v[88:89] op_sel_hi:[1,0,1]
	v_pk_fma_f32 v[90:91], v[148:149], s[42:43], v[90:91] op_sel_hi:[1,0,1]
	global_store_dwordx4 v[96:97], v[88:91], off
	ds_read_b128 v[88:91], v132 offset:2080
	v_pk_fma_f32 v[94:95], v[144:145], s[42:43], v[94:95] op_sel_hi:[1,0,1]
	global_store_dwordx4 v[98:99], v[92:95], off
	ds_read_b128 v[92:95], v132 offset:3120
	v_mov_b32_e32 v98, v150
	s_waitcnt vmcnt(14) lgkmcnt(1)
	v_pk_fma_f32 v[88:89], v[170:171], s[42:43], v[88:89] op_sel_hi:[1,0,1]
	v_pk_fma_f32 v[90:91], v[172:173], s[42:43], v[90:91] op_sel_hi:[1,0,1]
	global_store_dwordx4 v[100:101], v[88:91], off
	ds_read_b128 v[88:91], v132 offset:4160
	s_waitcnt lgkmcnt(1)
	v_pk_fma_f32 v[92:93], v[166:167], s[42:43], v[92:93] op_sel_hi:[1,0,1]
	v_pk_fma_f32 v[94:95], v[168:169], s[42:43], v[94:95] op_sel_hi:[1,0,1]
	global_store_dwordx4 v[102:103], v[92:95], off
	ds_read_b128 v[92:95], v132 offset:5200
	s_waitcnt vmcnt(14) lgkmcnt(1)
	v_pk_fma_f32 v[88:89], v[178:179], s[42:43], v[88:89] op_sel_hi:[1,0,1]
	v_pk_fma_f32 v[90:91], v[180:181], s[42:43], v[90:91] op_sel_hi:[1,0,1]
	global_store_dwordx4 v[104:105], v[88:91], off
	ds_read_b128 v[88:91], v132 offset:6240
	s_waitcnt lgkmcnt(1)
	v_pk_fma_f32 v[92:93], v[174:175], s[42:43], v[92:93] op_sel_hi:[1,0,1]
	v_pk_fma_f32 v[94:95], v[176:177], s[42:43], v[94:95] op_sel_hi:[1,0,1]
	global_store_dwordx4 v[106:107], v[92:95], off
	ds_read_b128 v[92:95], v132 offset:7280
	s_waitcnt vmcnt(14) lgkmcnt(1)
	v_pk_fma_f32 v[88:89], v[186:187], s[42:43], v[88:89] op_sel_hi:[1,0,1]
	v_pk_fma_f32 v[90:91], v[188:189], s[42:43], v[90:91] op_sel_hi:[1,0,1]
	global_store_dwordx4 v[108:109], v[88:91], off
	ds_read_b128 v[88:91], v132 offset:8320
	s_waitcnt lgkmcnt(1)
	v_pk_fma_f32 v[92:93], v[182:183], s[42:43], v[92:93] op_sel_hi:[1,0,1]
	v_pk_fma_f32 v[94:95], v[184:185], s[42:43], v[94:95] op_sel_hi:[1,0,1]
	global_store_dwordx4 v[110:111], v[92:95], off
	ds_read_b128 v[92:95], v132 offset:9360
	s_waitcnt vmcnt(14) lgkmcnt(1)
	v_pk_fma_f32 v[88:89], v[194:195], s[42:43], v[88:89] op_sel_hi:[1,0,1]
	v_pk_fma_f32 v[90:91], v[196:197], s[42:43], v[90:91] op_sel_hi:[1,0,1]
	global_store_dwordx4 v[112:113], v[88:91], off
	ds_read_b128 v[88:91], v132 offset:10400
	s_waitcnt lgkmcnt(1)
	v_pk_fma_f32 v[92:93], v[190:191], s[42:43], v[92:93] op_sel_hi:[1,0,1]
	v_pk_fma_f32 v[94:95], v[192:193], s[42:43], v[94:95] op_sel_hi:[1,0,1]
	global_store_dwordx4 v[114:115], v[92:95], off
	ds_read_b128 v[92:95], v132 offset:11440
	s_waitcnt vmcnt(14) lgkmcnt(1)
	v_pk_fma_f32 v[68:69], v[68:69], s[42:43], v[88:89] op_sel_hi:[1,0,1]
	v_pk_fma_f32 v[70:71], v[70:71], s[42:43], v[90:91] op_sel_hi:[1,0,1]
	global_store_dwordx4 v[116:117], v[68:71], off
	ds_read_b128 v[68:71], v132 offset:12480
	s_waitcnt lgkmcnt(1)
	v_pk_fma_f32 v[64:65], v[64:65], s[42:43], v[92:93] op_sel_hi:[1,0,1]
	v_pk_fma_f32 v[66:67], v[66:67], s[42:43], v[94:95] op_sel_hi:[1,0,1]
	global_store_dwordx4 v[118:119], v[64:67], off
	ds_read_b128 v[64:67], v132 offset:13520
	s_waitcnt vmcnt(14) lgkmcnt(1)
	v_pk_fma_f32 v[68:69], v[76:77], s[42:43], v[68:69] op_sel_hi:[1,0,1]
	v_pk_fma_f32 v[70:71], v[78:79], s[42:43], v[70:71] op_sel_hi:[1,0,1]
	global_store_dwordx4 v[120:121], v[68:71], off
	ds_read_b128 v[68:71], v132 offset:14560
	s_waitcnt lgkmcnt(1)
	v_pk_fma_f32 v[64:65], v[72:73], s[42:43], v[64:65] op_sel_hi:[1,0,1]
	v_pk_fma_f32 v[66:67], v[74:75], s[42:43], v[66:67] op_sel_hi:[1,0,1]
	ds_read_b128 v[72:75], v132 offset:15600
	global_store_dwordx4 v[122:123], v[64:67], off
	v_mov_b32_e32 v91, v133
	s_waitcnt vmcnt(14) lgkmcnt(1)
	v_pk_fma_f32 v[64:65], v[84:85], s[42:43], v[68:69] op_sel_hi:[1,0,1]
	v_pk_fma_f32 v[66:67], v[86:87], s[42:43], v[70:71] op_sel_hi:[1,0,1]
	global_store_dwordx4 v[124:125], v[64:67], off
	s_waitcnt lgkmcnt(0)
	s_nop 0
	v_pk_fma_f32 v[64:65], v[80:81], s[42:43], v[72:73] op_sel_hi:[1,0,1]
	v_pk_fma_f32 v[66:67], v[82:83], s[42:43], v[74:75] op_sel_hi:[1,0,1]
	global_store_dwordx4 v[126:127], v[64:67], off
	s_waitcnt lgkmcnt(0)
	s_barrier
; template <int MODE, int N>
; __device__ __forceinline__ void gemm_phase(const bf16_t* __restrict__ A, const bf16_t* __restrict__ Bt,
;                            bf16_t* __restrict__ Cb, float* __restrict__ Cf, const float* __restrict__ resid,
;                            float alpha) {
;     ...
;       for (int ai = 0; ai < 2; ++ai) {
;         int el = gtid;
;         asm volatile("" : "+v"(el));
;         const int ln = el & 63, rl0 = (el >> 6) * 16;
;         const unsigned goff = (unsigned)((brow + ai * HALF + rl0) * N + bcol + ln * 4);
;         float4 rr[16];
; #pragma unroll
;         for (int i = 0; i < 16; ++i) rr[i] = *(const float4*)(resid + (goff + (unsigned)(i * N)));
;         {
;           char* lb = cst + (((el >> 8) & 1) * 64 + (el & 15)) * FROW + (((el >> 6) & 3) * 32 + ((el >> 4) & 3) * 4) * 4;
;           for (int bj = 0; bj < 2; ++bj)
;             for (int m = 0; m < 4; ++m)
;               for (int n = 0; n < 2; ++n)
;                 *(f32x4*)(lb + m * 16 * FROW + bj * HALF * 4 + n * 64) = acc[ai][bj][m][n];
;         }
	v_mov_b32_e32 v75, v133
	v_and_b32_e32 v178, 63, v98
	v_ashrrev_i32_e32 v179, 6, v98
	v_lshlrev_b32_e32 v64, 16, v179
	v_lshlrev_b32_e32 v65, 2, v178
	v_add3_u32 v132, s44, v64, v65
	v_add_u32_e32 v66, 0x2000, v132
	v_mov_b32_e32 v67, v133
	v_lshlrev_b64 v[108:109], 2, v[66:67]
	v_add_u32_e32 v66, 0x3000, v132
	v_lshlrev_b64 v[110:111], 2, v[66:67]
	v_add_u32_e32 v66, 0x4000, v132
	v_lshlrev_b64 v[112:113], 2, v[66:67]
	v_add_u32_e32 v66, 0x5000, v132
	v_lshlrev_b64 v[114:115], 2, v[66:67]
	v_add_u32_e32 v66, 0x6000, v132
	v_lshlrev_b64 v[116:117], 2, v[66:67]
	v_add_u32_e32 v66, 0x7000, v132
	v_add_u32_e32 v64, 0x1000, v132
	v_mov_b32_e32 v65, v133
	v_lshlrev_b64 v[118:119], 2, v[66:67]
	v_add_u32_e32 v66, 0x8000, v132
	v_lshlrev_b64 v[104:105], 2, v[132:133]
	v_lshlrev_b64 v[106:107], 2, v[64:65]
	v_lshlrev_b64 v[120:121], 2, v[66:67]
	v_add_u32_e32 v66, 0x9000, v132
	v_lshl_add_u64 v[68:69], s[10:11], 0, v[104:105]
	v_lshl_add_u64 v[64:65], s[10:11], 0, v[106:107]
	v_lshlrev_b64 v[122:123], 2, v[66:67]
	v_add_u32_e32 v66, 0xa000, v132
	v_lshlrev_b64 v[124:125], 2, v[66:67]
	global_load_dwordx4 v[64:67], v[64:65], off
	s_nop 0
	global_load_dwordx4 v[68:71], v[68:69], off
	v_add_u32_e32 v74, 0xb000, v132
	v_lshl_add_u64 v[76:77], s[10:11], 0, v[108:109]
	v_lshl_add_u64 v[72:73], s[10:11], 0, v[110:111]
	v_lshlrev_b64 v[142:143], 2, v[74:75]
	v_add_u32_e32 v74, 0xc000, v132
	v_lshlrev_b64 v[146:147], 2, v[74:75]
	global_load_dwordx4 v[72:75], v[72:73], off
	s_nop 0
	global_load_dwordx4 v[76:79], v[76:77], off
	v_lshl_add_u64 v[84:85], s[10:11], 0, v[112:113]
	v_lshl_add_u64 v[80:81], s[10:11], 0, v[114:115]
	v_add_u32_e32 v82, 0xd000, v132
	v_mov_b32_e32 v83, v133
	v_lshlrev_b64 v[166:167], 2, v[82:83]
	global_load_dwordx4 v[80:83], v[80:81], off
	s_nop 0
	global_load_dwordx4 v[84:87], v[84:85], off
	v_lshl_add_u64 v[92:93], s[10:11], 0, v[116:117]
	v_lshl_add_u64 v[88:89], s[10:11], 0, v[118:119]
	v_add_u32_e32 v90, 0xe000, v132
	v_lshlrev_b64 v[170:171], 2, v[90:91]
	global_load_dwordx4 v[88:91], v[88:89], off
	s_nop 0
	global_load_dwordx4 v[92:95], v[92:93], off
	v_lshrrev_b32_e32 v99, 2, v98
	v_and_b32_e32 v102, 15, v98
	v_add_u32_e32 v132, 0xf000, v132
	v_and_or_b32 v99, v99, 64, v102
	v_lshl_add_u64 v[100:101], s[10:11], 0, v[120:121]
	v_lshl_add_u64 v[96:97], s[10:11], 0, v[122:123]
	v_lshlrev_b64 v[174:175], 2, v[132:133]
	v_mad_u32_u24 v132, v99, s59, 16
	v_lshlrev_b32_e32 v99, 7, v179
	v_and_b32_e32 v180, 0x180, v99
	v_and_b32_e32 v181, 48, v98
	global_load_dwordx4 v[96:99], v[96:97], off
	s_nop 0
	global_load_dwordx4 v[100:103], v[100:101], off
	v_add3_u32 v132, v132, v180, v181
	v_lshl_add_u64 v[144:145], s[10:11], 0, v[142:143]
	ds_write_b128 v132, v[0:3]
	ds_write_b128 v132, v[4:7] offset:64
	ds_write_b128 v132, v[8:11] offset:16640
	ds_write_b128 v132, v[12:15] offset:16704
	ds_write_b128 v132, v[20:23] offset:33280
	v_lshl_add_u64 v[126:127], s[10:11], 0, v[124:125]
	global_load_dwordx4 v[0:3], v[144:145], off
	global_load_dwordx4 v[4:7], v[126:127], off
	v_lshl_add_u64 v[168:169], s[10:11], 0, v[166:167]
	ds_write_b128 v132, v[16:19] offset:33344
	ds_write_b128 v132, v[24:27] offset:49920
	ds_write_b128 v132, v[28:31] offset:49984
	ds_write_b128 v132, v[32:35] offset:512
	ds_write_b128 v132, v[36:39] offset:576
	ds_write_b128 v132, v[44:47] offset:17152
	v_lshl_add_u64 v[148:149], s[10:11], 0, v[146:147]
	global_load_dwordx4 v[8:11], v[168:169], off
	global_load_dwordx4 v[12:15], v[148:149], off
	v_lshl_add_u64 v[176:177], s[10:11], 0, v[174:175]
	ds_write_b128 v132, v[40:43] offset:17216
	ds_write_b128 v132, v[48:51] offset:33792
	ds_write_b128 v132, v[52:55] offset:33856
	ds_write_b128 v132, v[56:59] offset:50432
	ds_write_b128 v132, v[60:63] offset:50496
	v_lshl_add_u64 v[172:173], s[10:11], 0, v[170:171]
	global_load_dwordx4 v[16:19], v[176:177], off
	global_load_dwordx4 v[20:23], v[172:173], off
	v_mul_lo_u32 v24, v179, s60
	v_lshlrev_b32_e32 v25, 4, v178
	v_add3_u32 v126, 16, v24, v25
	s_waitcnt lgkmcnt(0)
	s_barrier
; #define WAIT_L(n) asm volatile("s_waitcnt lgkmcnt(" #n ")" ::: "memory")
; #define BAR __builtin_amdgcn_s_barrier()
; template <int MODE, int N>
; __device__ __forceinline__ void gemm_phase(const bf16_t* __restrict__ A, const bf16_t* __restrict__ Bt,
;                            bf16_t* __restrict__ Cb, float* __restrict__ Cf, const float* __restrict__ resid,
;                            float alpha) {
;     ...
;         WAIT_L(0);
;         BAR;
;         asm volatile("" ::: "memory");
;         {
;           const char* lptr = cst + rl0 * FROW + ln * 16;
; #pragma unroll
;           for (int i = 0; i < 16; ++i) {
;             f32x4 v = *(const f32x4*)(lptr + i * FROW);
;             float4 o;
;             o.x = alpha * rr[i].x + v[0]; o.y = alpha * rr[i].y + v[1]; o.z = alpha * rr[i].z + v[2]; o.w = alpha * rr[i].w + v[3];
;             *(float4*)(Cf + (goff + (unsigned)(i * N))) = o;
;           }
;         }
;         WAIT_L(0);
;         BAR;
;         asm volatile("" ::: "memory");
;       }
;       if (tile + (int)gridDim.x < nwg) {
;         TILE_COORDS(tile + (int)gridDim.x, nbrow, nbcol);
;         PROLOGUE_ISSUE(nbrow, nbcol);
;       }
	ds_read_b128 v[24:27], v126
	ds_read_b128 v[28:31], v126 offset:1040
	v_lshl_add_u64 v[32:33], s[8:9], 0, v[104:105]
	v_lshl_add_u64 v[34:35], s[8:9], 0, v[106:107]
	v_lshl_add_u64 v[36:37], s[8:9], 0, v[108:109]
	v_lshl_add_u64 v[38:39], s[8:9], 0, v[110:111]
	v_lshl_add_u64 v[40:41], s[8:9], 0, v[112:113]
	v_lshl_add_u64 v[42:43], s[8:9], 0, v[114:115]
	v_lshl_add_u64 v[44:45], s[8:9], 0, v[116:117]
	v_lshl_add_u64 v[46:47], s[8:9], 0, v[118:119]
	v_lshl_add_u64 v[48:49], s[8:9], 0, v[120:121]
	v_lshl_add_u64 v[50:51], s[8:9], 0, v[122:123]
	v_lshl_add_u64 v[52:53], s[8:9], 0, v[124:125]
	v_lshl_add_u64 v[54:55], s[8:9], 0, v[142:143]
	v_lshl_add_u64 v[56:57], s[8:9], 0, v[146:147]
	v_lshl_add_u64 v[58:59], s[8:9], 0, v[166:167]
	v_lshl_add_u64 v[60:61], s[8:9], 0, v[170:171]
	v_lshl_add_u64 v[62:63], s[8:9], 0, v[174:175]
	s_mov_b32 s44, 0
	s_waitcnt vmcnt(15) lgkmcnt(0)
	v_pk_fma_f32 v[28:29], v[64:65], s[42:43], v[28:29] op_sel_hi:[1,0,1]
	s_waitcnt vmcnt(14)
	v_pk_fma_f32 v[24:25], v[68:69], s[42:43], v[24:25] op_sel_hi:[1,0,1]
	v_pk_fma_f32 v[26:27], v[70:71], s[42:43], v[26:27] op_sel_hi:[1,0,1]
	global_store_dwordx4 v[32:33], v[24:27], off
	ds_read_b128 v[24:27], v126 offset:2080
	v_pk_fma_f32 v[30:31], v[66:67], s[42:43], v[30:31] op_sel_hi:[1,0,1]
	global_store_dwordx4 v[34:35], v[28:31], off
	ds_read_b128 v[28:31], v126 offset:3120
	s_waitcnt vmcnt(14) lgkmcnt(1)
	v_pk_fma_f32 v[24:25], v[76:77], s[42:43], v[24:25] op_sel_hi:[1,0,1]
	v_pk_fma_f32 v[26:27], v[78:79], s[42:43], v[26:27] op_sel_hi:[1,0,1]
	global_store_dwordx4 v[36:37], v[24:27], off
	ds_read_b128 v[24:27], v126 offset:4160
	s_waitcnt lgkmcnt(1)
	v_pk_fma_f32 v[28:29], v[72:73], s[42:43], v[28:29] op_sel_hi:[1,0,1]
	v_pk_fma_f32 v[30:31], v[74:75], s[42:43], v[30:31] op_sel_hi:[1,0,1]
	global_store_dwordx4 v[38:39], v[28:31], off
	ds_read_b128 v[28:31], v126 offset:5200
	s_waitcnt vmcnt(14) lgkmcnt(1)
	v_pk_fma_f32 v[24:25], v[84:85], s[42:43], v[24:25] op_sel_hi:[1,0,1]
	v_pk_fma_f32 v[26:27], v[86:87], s[42:43], v[26:27] op_sel_hi:[1,0,1]
	global_store_dwordx4 v[40:41], v[24:27], off
	ds_read_b128 v[24:27], v126 offset:6240
	s_waitcnt lgkmcnt(1)
	v_pk_fma_f32 v[28:29], v[80:81], s[42:43], v[28:29] op_sel_hi:[1,0,1]
	v_pk_fma_f32 v[30:31], v[82:83], s[42:43], v[30:31] op_sel_hi:[1,0,1]
	global_store_dwordx4 v[42:43], v[28:31], off
	ds_read_b128 v[28:31], v126 offset:7280
	s_waitcnt vmcnt(14) lgkmcnt(1)
	v_pk_fma_f32 v[24:25], v[92:93], s[42:43], v[24:25] op_sel_hi:[1,0,1]
	v_pk_fma_f32 v[26:27], v[94:95], s[42:43], v[26:27] op_sel_hi:[1,0,1]
	global_store_dwordx4 v[44:45], v[24:27], off
	ds_read_b128 v[24:27], v126 offset:8320
	s_waitcnt lgkmcnt(1)
	v_pk_fma_f32 v[28:29], v[88:89], s[42:43], v[28:29] op_sel_hi:[1,0,1]
	v_pk_fma_f32 v[30:31], v[90:91], s[42:43], v[30:31] op_sel_hi:[1,0,1]
	global_store_dwordx4 v[46:47], v[28:31], off
	ds_read_b128 v[28:31], v126 offset:9360
	s_waitcnt vmcnt(14) lgkmcnt(1)
	v_pk_fma_f32 v[24:25], v[100:101], s[42:43], v[24:25] op_sel_hi:[1,0,1]
	v_pk_fma_f32 v[26:27], v[102:103], s[42:43], v[26:27] op_sel_hi:[1,0,1]
	global_store_dwordx4 v[48:49], v[24:27], off
	ds_read_b128 v[24:27], v126 offset:10400
	s_waitcnt lgkmcnt(1)
	v_pk_fma_f32 v[28:29], v[96:97], s[42:43], v[28:29] op_sel_hi:[1,0,1]
	v_pk_fma_f32 v[30:31], v[98:99], s[42:43], v[30:31] op_sel_hi:[1,0,1]
	global_store_dwordx4 v[50:51], v[28:31], off
	ds_read_b128 v[28:31], v126 offset:11440
	s_waitcnt vmcnt(14) lgkmcnt(1)
	v_pk_fma_f32 v[4:5], v[4:5], s[42:43], v[24:25] op_sel_hi:[1,0,1]
	v_pk_fma_f32 v[6:7], v[6:7], s[42:43], v[26:27] op_sel_hi:[1,0,1]
	global_store_dwordx4 v[52:53], v[4:7], off
	ds_read_b128 v[4:7], v126 offset:12480
	s_waitcnt lgkmcnt(1)
	v_pk_fma_f32 v[0:1], v[0:1], s[42:43], v[28:29] op_sel_hi:[1,0,1]
	v_pk_fma_f32 v[2:3], v[2:3], s[42:43], v[30:31] op_sel_hi:[1,0,1]
	global_store_dwordx4 v[54:55], v[0:3], off
	ds_read_b128 v[0:3], v126 offset:13520
	s_waitcnt vmcnt(14) lgkmcnt(1)
	v_pk_fma_f32 v[4:5], v[12:13], s[42:43], v[4:5] op_sel_hi:[1,0,1]
	v_pk_fma_f32 v[6:7], v[14:15], s[42:43], v[6:7] op_sel_hi:[1,0,1]
	global_store_dwordx4 v[56:57], v[4:7], off
	ds_read_b128 v[4:7], v126 offset:14560
	s_waitcnt lgkmcnt(1)
	v_pk_fma_f32 v[0:1], v[8:9], s[42:43], v[0:1] op_sel_hi:[1,0,1]
	v_pk_fma_f32 v[2:3], v[10:11], s[42:43], v[2:3] op_sel_hi:[1,0,1]
	ds_read_b128 v[8:11], v126 offset:15600
	global_store_dwordx4 v[58:59], v[0:3], off
	s_waitcnt vmcnt(14) lgkmcnt(1)
	s_nop 0
	v_pk_fma_f32 v[0:1], v[20:21], s[42:43], v[4:5] op_sel_hi:[1,0,1]
	v_pk_fma_f32 v[2:3], v[22:23], s[42:43], v[6:7] op_sel_hi:[1,0,1]
	global_store_dwordx4 v[60:61], v[0:3], off
	s_waitcnt lgkmcnt(0)
	s_nop 0
	v_pk_fma_f32 v[0:1], v[16:17], s[42:43], v[8:9] op_sel_hi:[1,0,1]
	v_pk_fma_f32 v[2:3], v[18:19], s[42:43], v[10:11] op_sel_hi:[1,0,1]
	global_store_dwordx4 v[62:63], v[0:3], off
	s_waitcnt lgkmcnt(0)
	s_barrier
	s_cbranch_vccnz .LBB0_727
	s_ashr_i32 s44, s2, 31
	s_lshr_b32 s44, s44, 29
	s_add_i32 s46, s2, s44
	s_and_b32 s44, s46, -8
	s_sub_i32 s61, s2, s44
	s_cmp_gt_i32 s61, -1
	s_mov_b64 s[44:45], -1
	s_cbranch_scc0 .LBB0_737
	s_lshl_b32 s47, s61, 6
	s_mov_b64 s[44:45], 0
